# MLA sample loop: row max over raw scores, one scale multiply per row tile (identical value), 60 fewer VALU per two key tiles
# baseline (speedup 1.0000x reference)
.LBB0_1440:
	ds_read_b128 v[116:119], v155
	ds_read_b128 v[120:123], v155 offset:64
	ds_read_b128 v[124:127], v155 offset:128
	ds_read_b128 v[128:131], v155 offset:192
	ds_read_b128 v[132:135], v155 offset:4352
	ds_read_b128 v[136:139], v155 offset:4416
	ds_read_b128 v[140:143], v155 offset:4480
	ds_read_b128 v[144:147], v155 offset:4544
	ds_read_b128 v[172:175], v155 offset:8704
	ds_read_b128 v[180:183], v155 offset:8768
	ds_read_b128 v[184:187], v155 offset:8832
	ds_read_b128 v[188:191], v155 offset:8896
	ds_read_b128 v[192:195], v155 offset:13056
	ds_read_b128 v[196:199], v155 offset:13120
	ds_read_b128 v[200:203], v155 offset:13184
	ds_read_b128 v[204:207], v155 offset:13248
	s_waitcnt lgkmcnt(14)
	v_mfma_f32_16x16x32_bf16 v[216:219], v[116:119], v[4:7], 0
	v_and_b32_e32 v2, 64, v215
	v_xor_b32_e32 v0, 16, v215
	v_add_u32_e32 v2, 64, v2
	v_mfma_f32_16x16x32_bf16 v[116:119], v[116:119], v[20:23], 0
	v_cmp_lt_i32_e32 vcc, v0, v2
	v_mfma_f32_16x16x32_bf16 v[216:219], v[120:123], v[8:11], v[216:219]
	s_nop 0
	v_cndmask_b32_e32 v0, v215, v0, vcc
	v_lshlrev_b32_e32 v169, 2, v0
	v_xor_b32_e32 v0, 32, v215
	v_mfma_f32_16x16x32_bf16 v[116:119], v[120:123], v[24:27], v[116:119]
	v_cmp_lt_i32_e32 vcc, v0, v2
	s_waitcnt lgkmcnt(13)
	v_mfma_f32_16x16x32_bf16 v[120:123], v[124:127], v[12:15], v[216:219]
	v_cndmask_b32_e32 v0, v215, v0, vcc
	v_lshlrev_b32_e32 v168, 2, v0
	v_mfma_f32_16x16x32_bf16 v[116:119], v[124:127], v[28:31], v[116:119]
	s_waitcnt lgkmcnt(12)
	v_mfma_f32_16x16x32_bf16 v[216:219], v[128:131], v[16:19], v[120:123]
	v_mfma_f32_16x16x32_bf16 v[120:123], v[128:131], v[32:35], v[116:119]
	s_waitcnt lgkmcnt(11)
	v_mfma_f32_16x16x32_bf16 v[116:119], v[132:135], v[4:7], 0
	s_nop 4
	s_nop 0
	s_nop 0
	v_max3_f32 v0, v216, s82, v217
	v_mfma_f32_16x16x32_bf16 v[124:127], v[132:135], v[20:23], 0
	s_nop 0
	s_nop 0
	v_max3_f32 v0, v0, v218, v219
	s_waitcnt lgkmcnt(10)
	v_mfma_f32_16x16x32_bf16 v[116:119], v[136:139], v[8:11], v[116:119]
	v_mfma_f32_16x16x32_bf16 v[124:127], v[136:139], v[24:27], v[124:127]
	s_waitcnt lgkmcnt(9)
	v_mfma_f32_16x16x32_bf16 v[116:119], v[140:143], v[12:15], v[116:119]
	v_mfma_f32_16x16x32_bf16 v[124:127], v[140:143], v[28:31], v[124:127]
	s_waitcnt lgkmcnt(8)
	v_mfma_f32_16x16x32_bf16 v[140:143], v[144:147], v[16:19], v[116:119]
	s_waitcnt lgkmcnt(7)
	v_mfma_f32_16x16x32_bf16 v[116:119], v[172:175], v[4:7], 0
	s_waitcnt lgkmcnt(6)
	v_mfma_f32_16x16x32_bf16 v[116:119], v[180:183], v[8:11], v[116:119]
	s_nop 3
	s_nop 0
	s_nop 0
	v_max3_f32 v0, v0, v140, v141
	s_waitcnt lgkmcnt(5)
	v_mfma_f32_16x16x32_bf16 v[116:119], v[184:187], v[12:15], v[116:119]
	s_nop 0
	s_nop 0
	v_max3_f32 v0, v0, v142, v143
	s_waitcnt lgkmcnt(4)
	v_mfma_f32_16x16x32_bf16 v[136:139], v[188:191], v[16:19], v[116:119]
	s_waitcnt lgkmcnt(3)
	v_mfma_f32_16x16x32_bf16 v[116:119], v[192:195], v[4:7], 0
	v_mfma_f32_16x16x32_bf16 v[132:135], v[192:195], v[20:23], 0
	s_nop 4
	s_nop 0
	s_nop 0
	v_max3_f32 v0, v0, v136, v137
	s_waitcnt lgkmcnt(2)
	v_mfma_f32_16x16x32_bf16 v[116:119], v[196:199], v[8:11], v[116:119]
	s_nop 0
	s_nop 0
	v_max3_f32 v0, v0, v138, v139
	v_mfma_f32_16x16x32_bf16 v[132:135], v[196:199], v[24:27], v[132:135]
	s_waitcnt lgkmcnt(1)
	v_mfma_f32_16x16x32_bf16 v[116:119], v[200:203], v[12:15], v[116:119]
	v_mfma_f32_16x16x32_bf16 v[128:131], v[144:147], v[32:35], v[124:127]
	v_mfma_f32_16x16x32_bf16 v[144:147], v[200:203], v[28:31], v[132:135]
	s_waitcnt lgkmcnt(0)
	v_mfma_f32_16x16x32_bf16 v[132:135], v[204:207], v[16:19], v[116:119]
	v_mfma_f32_16x16x32_bf16 v[124:127], v[172:175], v[20:23], 0
	v_mfma_f32_16x16x32_bf16 v[124:127], v[180:183], v[24:27], v[124:127]
	s_nop 5
	s_nop 0
	s_nop 0
	v_max3_f32 v0, v0, v132, v133
	s_nop 0
	s_nop 0
	v_max3_f32 v0, v0, v134, v135
	v_mul_f32_e32 v0, 0x3e0293ee, v0
	v_mov_b32_e32 v2, v0
	v_mfma_f32_16x16x32_bf16 v[124:127], v[184:187], v[28:31], v[124:127]
	s_waitcnt lgkmcnt(0)
	s_nop 1
	v_permlane16_swap_b32_e32 v2, v0
	v_max_f32_e32 v0, v0, v2
	v_mov_b32_e32 v2, v0
	v_mfma_f32_16x16x32_bf16 v[124:127], v[188:191], v[32:35], v[124:127]
	s_waitcnt lgkmcnt(0)
	s_nop 1
	v_permlane32_swap_b32_e32 v2, v0
	v_max3_f32 v0, v170, v0, v2
	v_fma_f32 v2, v216, s74, -v0
	v_exp_f32_e32 v173, v2
	v_fma_f32 v3, v217, s74, -v0
	v_exp_f32_e32 v174, v3
	v_fma_f32 v3, v218, s74, -v0
	v_exp_f32_e32 v175, v3
	v_fma_f32 v3, v219, s74, -v0
	v_exp_f32_e32 v176, v3
	v_fma_f32 v3, v140, s74, -v0
	v_add_f32_e32 v2, 0, v173
	v_exp_f32_e32 v177, v3
	v_fma_f32 v3, v141, s74, -v0
	v_add_f32_e32 v2, v174, v2
	v_exp_f32_e32 v180, v3
	v_fma_f32 v3, v142, s74, -v0
	v_add_f32_e32 v2, v175, v2
	v_exp_f32_e32 v181, v3
	v_fma_f32 v3, v143, s74, -v0
	v_add_f32_e32 v2, v176, v2
	v_exp_f32_e32 v183, v3
	v_fma_f32 v3, v136, s74, -v0
	v_add_f32_e32 v2, v177, v2
	v_exp_f32_e32 v182, v3
	v_fma_f32 v3, v137, s74, -v0
	v_add_f32_e32 v2, v180, v2
	v_exp_f32_e32 v184, v3
	v_fma_f32 v3, v138, s74, -v0
	v_add_f32_e32 v2, v181, v2
	v_exp_f32_e32 v185, v3
	v_fma_f32 v3, v139, s74, -v0
	v_add_f32_e32 v2, v183, v2
	v_exp_f32_e32 v186, v3
	v_fma_f32 v3, v132, s74, -v0
	v_add_f32_e32 v2, v182, v2
	v_exp_f32_e32 v187, v3
	v_fma_f32 v3, v133, s74, -v0
	v_add_f32_e32 v2, v184, v2
	v_exp_f32_e32 v188, v3
	v_fma_f32 v3, v134, s74, -v0
	v_add_f32_e32 v2, v185, v2
	v_exp_f32_e32 v189, v3
	v_fma_f32 v3, v135, s74, -v0
	v_add_f32_e32 v2, v186, v2
	v_exp_f32_e32 v190, v3
	v_mfma_f32_16x16x32_bf16 v[116:119], v[204:207], v[32:35], v[144:147]
	v_add_f32_e32 v2, v187, v2
	v_add_f32_e32 v2, v188, v2
	v_add_f32_e32 v2, v189, v2
	v_cmp_gt_f32_e32 vcc, v0, v170
	v_add_f32_e32 v2, v190, v2
	s_cbranch_vccz .LBB0_1456
	v_sub_f32_e32 v3, v170, v0
	v_exp_f32_e32 v144, v3
	v_mov_b32_e32 v159, v157
	v_fma_f32 v158, v156, v144, v2
	v_pk_mul_f32 v[134:135], v[114:115], v[144:145] op_sel_hi:[1,0]
	v_pk_mul_f32 v[132:133], v[112:113], v[144:145] op_sel_hi:[1,0]
	v_pk_mul_f32 v[138:139], v[110:111], v[144:145] op_sel_hi:[1,0]
	v_pk_mul_f32 v[136:137], v[108:109], v[144:145] op_sel_hi:[1,0]
	v_pk_mul_f32 v[142:143], v[106:107], v[144:145] op_sel_hi:[1,0]
	v_pk_mul_f32 v[140:141], v[104:105], v[144:145] op_sel_hi:[1,0]
	v_pk_mul_f32 v[146:147], v[102:103], v[144:145] op_sel_hi:[1,0]
	v_pk_mul_f32 v[144:145], v[100:101], v[144:145] op_sel_hi:[1,0]
	s_cbranch_execnz .LBB0_1443

.LBB0_1443:
	s_nop 0
	s_nop 0
	v_max3_f32 v2, v120, s82, v121
	s_nop 0
	s_nop 0
	v_max3_f32 v2, v2, v122, v123
	s_nop 0
	s_nop 0
	v_max3_f32 v2, v2, v128, v129
	s_nop 0
	s_nop 0
	v_max3_f32 v2, v2, v130, v131
	s_nop 0
	s_nop 0
	v_max3_f32 v2, v2, v124, v125
	s_nop 0
	s_nop 0
	v_max3_f32 v2, v2, v126, v127
	s_nop 0
	s_nop 0
	v_max3_f32 v2, v2, v116, v117
	s_nop 0
	s_nop 0
	v_max3_f32 v2, v2, v118, v119
	v_mul_f32_e32 v2, 0x3e0293ee, v2
	v_mov_b32_e32 v3, v2
	s_waitcnt lgkmcnt(0)
	s_nop 1
	v_permlane16_swap_b32_e32 v3, v2
	v_max_f32_e32 v2, v2, v3
	v_mov_b32_e32 v3, v2
	s_waitcnt lgkmcnt(0)
	s_nop 1
	v_permlane32_swap_b32_e32 v3, v2
	v_max3_f32 v172, v171, v2, v3
	v_fma_f32 v2, v120, s74, -v172
	v_exp_f32_e32 v120, v2
	v_fma_f32 v2, v121, s74, -v172
	v_exp_f32_e32 v121, v2
	v_fma_f32 v2, v122, s74, -v172
	v_exp_f32_e32 v122, v2
	v_fma_f32 v2, v123, s74, -v172
	v_exp_f32_e32 v123, v2
	v_fma_f32 v3, v128, s74, -v172
	v_add_f32_e32 v2, 0, v120
	v_exp_f32_e32 v128, v3
	v_fma_f32 v3, v129, s74, -v172
	v_add_f32_e32 v2, v121, v2
	v_exp_f32_e32 v129, v3
	v_fma_f32 v3, v130, s74, -v172
	v_add_f32_e32 v2, v122, v2
	v_exp_f32_e32 v130, v3
	v_fma_f32 v3, v131, s74, -v172
	v_add_f32_e32 v2, v123, v2
	v_exp_f32_e32 v131, v3
	v_fma_f32 v3, v124, s74, -v172
	v_add_f32_e32 v2, v128, v2
	v_exp_f32_e32 v124, v3
	v_fma_f32 v3, v125, s74, -v172
	v_add_f32_e32 v2, v129, v2
	v_exp_f32_e32 v125, v3
	v_fma_f32 v3, v126, s74, -v172
	v_add_f32_e32 v2, v130, v2
	v_exp_f32_e32 v126, v3
	v_fma_f32 v3, v127, s74, -v172
	v_add_f32_e32 v2, v131, v2
	v_exp_f32_e32 v127, v3
	v_fma_f32 v3, v116, s74, -v172
	v_add_f32_e32 v2, v124, v2
	v_exp_f32_e32 v116, v3
	v_fma_f32 v3, v117, s74, -v172
	v_add_f32_e32 v2, v125, v2
	v_exp_f32_e32 v117, v3
	v_fma_f32 v3, v118, s74, -v172
	v_add_f32_e32 v2, v126, v2
	v_exp_f32_e32 v118, v3
	v_fma_f32 v3, v119, s74, -v172
	v_add_f32_e32 v2, v127, v2
	v_exp_f32_e32 v119, v3
	v_add_f32_e32 v2, v116, v2
	v_add_f32_e32 v2, v117, v2
	v_add_f32_e32 v2, v118, v2
	v_cmp_gt_f32_e32 vcc, v172, v171
	v_add_f32_e32 v156, v119, v2
	s_cbranch_vccz .LBB0_1457
	v_sub_f32_e32 v2, v171, v172
	v_exp_f32_e32 v112, v2
	v_mov_b32_e32 v2, v158
	v_fma_f32 v3, v159, v112, v156
	v_pk_mul_f32 v[102:103], v[98:99], v[112:113] op_sel_hi:[1,0]
	v_pk_mul_f32 v[100:101], v[96:97], v[112:113] op_sel_hi:[1,0]
	v_pk_mul_f32 v[106:107], v[94:95], v[112:113] op_sel_hi:[1,0]
	v_pk_mul_f32 v[104:105], v[92:93], v[112:113] op_sel_hi:[1,0]
	v_pk_mul_f32 v[110:111], v[90:91], v[112:113] op_sel_hi:[1,0]
	v_pk_mul_f32 v[108:109], v[88:89], v[112:113] op_sel_hi:[1,0]
	v_pk_mul_f32 v[114:115], v[86:87], v[112:113] op_sel_hi:[1,0]
	v_pk_mul_f32 v[112:113], v[84:85], v[112:113] op_sel_hi:[1,0]
	s_cbranch_execnz .LBB0_1446

.LBB0_1448:
	ds_read_b128 v[116:119], v155 offset:26624
	ds_read_b128 v[120:123], v155 offset:26688
	ds_read_b128 v[124:127], v155 offset:26752
	ds_read_b128 v[128:131], v155 offset:26816
	ds_read_b128 v[132:135], v155 offset:30976
	ds_read_b128 v[136:139], v155 offset:31040
	ds_read_b128 v[140:143], v155 offset:31104
	ds_read_b128 v[144:147], v155 offset:31168
	ds_read_b128 v[156:159], v155 offset:35328
	ds_read_b128 v[174:177], v155 offset:35392
	ds_read_b128 v[180:183], v155 offset:35456
	ds_read_b128 v[184:187], v155 offset:35520
	ds_read_b128 v[188:191], v155 offset:39680
	ds_read_b128 v[192:195], v155 offset:39744
	ds_read_b128 v[196:199], v155 offset:39808
	ds_read_b128 v[200:203], v155 offset:39872
	s_waitcnt lgkmcnt(14)
	v_mfma_f32_16x16x32_bf16 v[204:207], v[116:119], v[4:7], 0
	v_mfma_f32_16x16x32_bf16 v[116:119], v[116:119], v[20:23], 0
	v_mfma_f32_16x16x32_bf16 v[204:207], v[120:123], v[8:11], v[204:207]
	v_mfma_f32_16x16x32_bf16 v[116:119], v[120:123], v[24:27], v[116:119]
	s_waitcnt lgkmcnt(13)
	v_mfma_f32_16x16x32_bf16 v[120:123], v[124:127], v[12:15], v[204:207]
	s_waitcnt lgkmcnt(12)
	v_mfma_f32_16x16x32_bf16 v[204:207], v[128:131], v[16:19], v[120:123]
	s_waitcnt lgkmcnt(11)
	v_mfma_f32_16x16x32_bf16 v[120:123], v[132:135], v[4:7], 0
	s_waitcnt lgkmcnt(10)
	v_mfma_f32_16x16x32_bf16 v[120:123], v[136:139], v[8:11], v[120:123]
	v_mfma_f32_16x16x32_bf16 v[116:119], v[124:127], v[28:31], v[116:119]
	v_mfma_f32_16x16x32_bf16 v[124:127], v[132:135], v[20:23], 0
	s_waitcnt lgkmcnt(9)
	v_mfma_f32_16x16x32_bf16 v[120:123], v[140:143], v[12:15], v[120:123]
	v_mfma_f32_16x16x32_bf16 v[124:127], v[136:139], v[24:27], v[124:127]
	s_waitcnt lgkmcnt(8)
	v_mfma_f32_16x16x32_bf16 v[136:139], v[144:147], v[16:19], v[120:123]
	s_waitcnt lgkmcnt(7)
	v_mfma_f32_16x16x32_bf16 v[120:123], v[156:159], v[4:7], 0
	s_waitcnt lgkmcnt(6)
	v_mfma_f32_16x16x32_bf16 v[120:123], v[174:177], v[8:11], v[120:123]
	s_waitcnt lgkmcnt(5)
	v_mfma_f32_16x16x32_bf16 v[120:123], v[180:183], v[12:15], v[120:123]
	v_mfma_f32_16x16x32_bf16 v[124:127], v[140:143], v[28:31], v[124:127]
	s_waitcnt lgkmcnt(4)
	v_mfma_f32_16x16x32_bf16 v[140:143], v[184:187], v[16:19], v[120:123]
	s_waitcnt lgkmcnt(3)
	v_mfma_f32_16x16x32_bf16 v[120:123], v[188:191], v[4:7], 0
	v_mfma_f32_16x16x32_bf16 v[132:135], v[188:191], v[20:23], 0
	s_waitcnt lgkmcnt(2)
	v_mfma_f32_16x16x32_bf16 v[120:123], v[192:195], v[8:11], v[120:123]
	v_mfma_f32_16x16x32_bf16 v[132:135], v[192:195], v[24:27], v[132:135]
	v_mfma_f32_16x16x32_bf16 v[124:127], v[144:147], v[32:35], v[124:127]
	s_waitcnt lgkmcnt(1)
	v_mfma_f32_16x16x32_bf16 v[120:123], v[196:199], v[12:15], v[120:123]
	v_mfma_f32_16x16x32_bf16 v[144:147], v[196:199], v[28:31], v[132:135]
	s_waitcnt lgkmcnt(0)
	v_mfma_f32_16x16x32_bf16 v[132:135], v[200:203], v[16:19], v[120:123]
	v_mfma_f32_16x16x32_bf16 v[120:123], v[200:203], v[32:35], v[144:147]
	s_nop 4
	s_nop 0
	s_nop 0
	v_max3_f32 v144, v204, s82, v205
	s_nop 0
	s_nop 0
	v_max3_f32 v144, v144, v206, v207
	s_nop 0
	s_nop 0
	v_max3_f32 v144, v144, v136, v137
	s_nop 0
	s_nop 0
	v_max3_f32 v144, v144, v138, v139
	s_nop 0
	s_nop 0
	v_max3_f32 v144, v144, v140, v141
	s_nop 0
	s_nop 0
	v_max3_f32 v144, v144, v142, v143
	s_nop 0
	s_nop 0
	v_max3_f32 v144, v144, v132, v133
	s_nop 0
	s_nop 0
	v_max3_f32 v144, v144, v134, v135
	v_mul_f32_e32 v144, 0x3e0293ee, v144
	v_mov_b32_e32 v145, v144
	v_mfma_f32_16x16x32_bf16 v[116:119], v[128:131], v[32:35], v[116:119]
	s_waitcnt lgkmcnt(0)
	s_nop 1
	v_permlane16_swap_b32_e32 v145, v144
	v_max_f32_e32 v144, v144, v145
	v_mov_b32_e32 v145, v144
	v_mfma_f32_16x16x32_bf16 v[128:131], v[156:159], v[20:23], 0
	s_waitcnt lgkmcnt(0)
	s_nop 1
	v_permlane32_swap_b32_e32 v145, v144
	v_max3_f32 v170, v0, v144, v145
	v_fma_f32 v144, v204, s74, -v170
	v_exp_f32_e32 v173, v144
	v_fma_f32 v145, v205, s74, -v170
	v_mfma_f32_16x16x32_bf16 v[128:131], v[174:177], v[24:27], v[128:131]
	v_exp_f32_e32 v174, v145
	v_fma_f32 v145, v206, s74, -v170
	v_exp_f32_e32 v175, v145
	v_fma_f32 v145, v207, s74, -v170
	v_exp_f32_e32 v176, v145
	v_fma_f32 v136, v136, s74, -v170
	v_add_f32_e32 v144, 0, v173
	v_exp_f32_e32 v177, v136
	v_fma_f32 v137, v137, s74, -v170
	v_mfma_f32_16x16x32_bf16 v[128:131], v[180:183], v[28:31], v[128:131]
	v_add_f32_e32 v144, v174, v144
	v_exp_f32_e32 v180, v137
	v_fma_f32 v137, v138, s74, -v170
	v_add_f32_e32 v144, v175, v144
	v_exp_f32_e32 v181, v137
	v_fma_f32 v137, v139, s74, -v170
	v_add_f32_e32 v144, v176, v144
	v_exp_f32_e32 v183, v137
	v_fma_f32 v137, v140, s74, -v170
	v_add_f32_e32 v136, v177, v144
	v_exp_f32_e32 v182, v137
	v_fma_f32 v137, v141, s74, -v170
	v_mfma_f32_16x16x32_bf16 v[128:131], v[184:187], v[32:35], v[128:131]
	v_add_f32_e32 v136, v180, v136
	v_exp_f32_e32 v184, v137
	v_fma_f32 v137, v142, s74, -v170
	v_add_f32_e32 v136, v181, v136
	v_exp_f32_e32 v185, v137
	v_fma_f32 v137, v143, s74, -v170
	v_add_f32_e32 v136, v183, v136
	v_exp_f32_e32 v186, v137
	v_fma_f32 v132, v132, s74, -v170
	v_add_f32_e32 v136, v182, v136
	v_exp_f32_e32 v187, v132
	v_fma_f32 v133, v133, s74, -v170
	v_add_f32_e32 v136, v184, v136
	v_exp_f32_e32 v188, v133
	v_fma_f32 v133, v134, s74, -v170
	v_add_f32_e32 v136, v185, v136
	v_exp_f32_e32 v189, v133
	v_fma_f32 v133, v135, s74, -v170
	v_add_f32_e32 v136, v186, v136
	v_exp_f32_e32 v190, v133
	v_add_f32_e32 v132, v187, v136
	v_add_f32_e32 v132, v188, v132
	v_add_f32_e32 v132, v189, v132
	v_cmp_gt_f32_e32 vcc, v170, v0
	v_add_f32_e32 v156, v190, v132
	s_cbranch_vccz .LBB0_1458
	v_sub_f32_e32 v132, v0, v170
	v_exp_f32_e32 v144, v132
	v_mov_b32_e32 v159, v3
	v_fma_f32 v158, v2, v144, v156
	v_pk_mul_f32 v[134:135], v[102:103], v[144:145] op_sel_hi:[1,0]
	v_pk_mul_f32 v[132:133], v[100:101], v[144:145] op_sel_hi:[1,0]
	v_pk_mul_f32 v[138:139], v[106:107], v[144:145] op_sel_hi:[1,0]
	v_pk_mul_f32 v[136:137], v[104:105], v[144:145] op_sel_hi:[1,0]
	v_pk_mul_f32 v[142:143], v[110:111], v[144:145] op_sel_hi:[1,0]
	v_pk_mul_f32 v[140:141], v[108:109], v[144:145] op_sel_hi:[1,0]
	v_pk_mul_f32 v[146:147], v[114:115], v[144:145] op_sel_hi:[1,0]
	v_pk_mul_f32 v[144:145], v[112:113], v[144:145] op_sel_hi:[1,0]
	s_cbranch_execnz .LBB0_1451

.LBB0_1451:
	s_nop 0
	s_nop 0
	v_max3_f32 v0, v116, s82, v117
	s_nop 0
	s_nop 0
	v_max3_f32 v0, v0, v118, v119
	s_nop 0
	s_nop 0
	v_max3_f32 v0, v0, v124, v125
	s_nop 0
	s_nop 0
	v_max3_f32 v0, v0, v126, v127
	s_nop 0
	s_nop 0
	v_max3_f32 v0, v0, v128, v129
	s_nop 0
	s_nop 0
	v_max3_f32 v0, v0, v130, v131
	s_nop 0
	s_nop 0
	v_max3_f32 v0, v0, v120, v121
	s_nop 0
	s_nop 0
	v_max3_f32 v0, v0, v122, v123
	v_mul_f32_e32 v0, 0x3e0293ee, v0
	v_mov_b32_e32 v2, v0
	s_waitcnt lgkmcnt(0)
	s_nop 1
	v_permlane16_swap_b32_e32 v2, v0
	v_max_f32_e32 v0, v0, v2
	v_mov_b32_e32 v2, v0
	s_waitcnt lgkmcnt(0)
	s_nop 1
	v_permlane32_swap_b32_e32 v2, v0
	v_max3_f32 v171, v172, v0, v2
	v_fma_f32 v0, v116, s74, -v171
	v_exp_f32_e32 v0, v0
	v_fma_f32 v2, v117, s74, -v171
	v_exp_f32_e32 v2, v2
	v_fma_f32 v3, v118, s74, -v171
	v_exp_f32_e32 v3, v3
	v_fma_f32 v100, v119, s74, -v171
	v_exp_f32_e32 v116, v100
	v_fma_f32 v101, v124, s74, -v171
	v_add_f32_e32 v100, 0, v0
	v_exp_f32_e32 v117, v101
	v_fma_f32 v101, v125, s74, -v171
	v_add_f32_e32 v100, v2, v100
	v_exp_f32_e32 v119, v101
	v_fma_f32 v101, v126, s74, -v171
	v_add_f32_e32 v100, v3, v100
	v_exp_f32_e32 v125, v101
	v_fma_f32 v101, v127, s74, -v171
	v_add_f32_e32 v100, v116, v100
	v_exp_f32_e32 v127, v101
	v_fma_f32 v101, v128, s74, -v171
	v_add_f32_e32 v100, v117, v100
	v_exp_f32_e32 v118, v101
	v_fma_f32 v101, v129, s74, -v171
	v_add_f32_e32 v100, v119, v100
	v_exp_f32_e32 v124, v101
	v_fma_f32 v101, v130, s74, -v171
	v_add_f32_e32 v100, v125, v100
	v_exp_f32_e32 v126, v101
	v_fma_f32 v101, v131, s74, -v171
	v_add_f32_e32 v100, v127, v100
	v_exp_f32_e32 v128, v101
	v_fma_f32 v101, v120, s74, -v171
	v_add_f32_e32 v100, v118, v100
	v_exp_f32_e32 v120, v101
	v_fma_f32 v101, v121, s74, -v171
	v_add_f32_e32 v100, v124, v100
	v_exp_f32_e32 v121, v101
	v_fma_f32 v101, v122, s74, -v171
	v_add_f32_e32 v100, v126, v100
	v_exp_f32_e32 v122, v101
	v_fma_f32 v101, v123, s74, -v171
	v_add_f32_e32 v100, v128, v100
	v_exp_f32_e32 v123, v101
	v_add_f32_e32 v100, v120, v100
	v_add_f32_e32 v100, v121, v100
	v_add_f32_e32 v100, v122, v100
	v_cmp_gt_f32_e32 vcc, v171, v172
	v_add_f32_e32 v129, v123, v100
	s_cbranch_vccz .LBB0_1459
	v_sub_f32_e32 v100, v172, v171
	v_exp_f32_e32 v112, v100
	v_mov_b32_e32 v156, v158
	v_fma_f32 v157, v159, v112, v129
	v_pk_mul_f32 v[102:103], v[86:87], v[112:113] op_sel_hi:[1,0]
	v_pk_mul_f32 v[100:101], v[84:85], v[112:113] op_sel_hi:[1,0]
	v_pk_mul_f32 v[106:107], v[90:91], v[112:113] op_sel_hi:[1,0]
	v_pk_mul_f32 v[104:105], v[88:89], v[112:113] op_sel_hi:[1,0]
	v_pk_mul_f32 v[110:111], v[94:95], v[112:113] op_sel_hi:[1,0]
	v_pk_mul_f32 v[108:109], v[92:93], v[112:113] op_sel_hi:[1,0]
	v_pk_mul_f32 v[114:115], v[98:99], v[112:113] op_sel_hi:[1,0]
	v_pk_mul_f32 v[112:113], v[96:97], v[112:113] op_sel_hi:[1,0]
	s_cbranch_execnz .LBB0_1454
